# P7 row sum-of-squares partial stores also write-through (sc1), leaving no dirty P7 lines for the P7->P8 write-back; otherwise v95
# baseline (speedup 1.0000x reference)
.LBB0_508:
	v_lshl_add_u32 v142, s10, 8, v144
	v_lshl_or_b32 v140, s62, 8, v146
	v_lshl_add_u32 v150, v142, 10, v140
	v_lshlrev_b32_e32 v154, 2, v150
	v_lshlrev_b32_e32 v165, 1, v150
	v_bfe_u32 v140, v254, 4, 1
	v_mul_u32_u24_e32 v140, 24, v140
	v_add_u32_e32 v165, v165, v140
	v_add_u32_e32 v155, 0x10000, v154
	v_add_u32_e32 v166, 0x8000, v165
	v_add_u32_e32 v156, 0x20000, v154
	v_add_u32_e32 v167, 0x10000, v165
	v_add_u32_e32 v157, 0x30000, v154
	v_add_u32_e32 v168, 0x18000, v165
	v_add_u32_e32 v158, 0x80000, v154
	v_add_u32_e32 v169, 0x40000, v165
	v_add_u32_e32 v159, 0x90000, v154
	v_add_u32_e32 v170, 0x48000, v165
	v_add_u32_e32 v160, 0xa0000, v154
	v_add_u32_e32 v171, 0x50000, v165
	v_add_u32_e32 v161, 0xb0000, v154
	v_add_u32_e32 v172, 0x58000, v165
	v_cmp_lt_i32_e32 vcc, v162, v163
	s_nop 1
	v_cndmask_b32_e32 v173, v181, v162, vcc
	v_lshlrev_b32_e32 v173, 2, v173
	v_cmp_lt_i32_e32 vcc, v164, v163
	s_nop 1
	v_cndmask_b32_e32 v174, v181, v164, vcc
	v_lshlrev_b32_e32 v174, 2, v174
	s_lshl_b32 s48, s62, 4
	s_lshl_b32 s49, s55, 2
	s_add_i32 s48, s48, s49
	v_lshl_add_u32 v180, v142, 6, s48
	v_add_u32_e32 v175, 0x2000, v180
	global_load_dwordx4 v[182:185], v154, s[36:37]
	global_load_dwordx4 v[186:189], v154, s[36:37] offset:64
	global_load_dwordx4 v[190:193], v154, s[36:37] offset:512
	global_load_dwordx4 v[194:197], v154, s[36:37] offset:576
	global_load_dwordx4 v[198:201], v155, s[36:37]
	global_load_dwordx4 v[202:205], v155, s[36:37] offset:64
	global_load_dwordx4 v[206:209], v155, s[36:37] offset:512
	global_load_dwordx4 v[210:213], v155, s[36:37] offset:576
	global_load_dwordx4 v[214:217], v156, s[36:37]
	global_load_dwordx4 v[218:221], v156, s[36:37] offset:64
	global_load_dwordx4 v[222:225], v156, s[36:37] offset:512
	global_load_dwordx4 v[226:229], v156, s[36:37] offset:576
	global_load_dwordx4 v[230:233], v157, s[36:37]
	global_load_dwordx4 v[234:237], v157, s[36:37] offset:64
	global_load_dwordx4 v[238:241], v157, s[36:37] offset:512
	global_load_dwordx4 v[242:245], v157, s[36:37] offset:576
	s_waitcnt vmcnt(15)
	v_add_f32_e32 v124, v124, v182
	v_add_f32_e32 v125, v125, v183
	v_add_f32_e32 v126, v126, v184
	v_add_f32_e32 v127, v127, v185
	global_store_dwordx4 v154, v[124:127], s[30:31] sc1
	v_cvt_pk_bf16_f32 v176, v124, v125
	v_cvt_pk_bf16_f32 v177, v126, v127
	v_mul_f32_e32 v150, v125, v125
	v_mul_f32_e32 v140, v127, v127
	v_fmac_f32_e32 v150, v124, v124
	v_fmac_f32_e32 v140, v126, v126
	v_add_f32_e32 v246, v150, v140
	global_load_dwordx4 v[182:185], v158, s[36:37]
	s_waitcnt vmcnt(16)
	v_add_f32_e32 v120, v120, v186
	v_add_f32_e32 v121, v121, v187
	v_add_f32_e32 v122, v122, v188
	v_add_f32_e32 v123, v123, v189
	global_store_dwordx4 v154, v[120:123], s[30:31] offset:64 sc1
	v_cvt_pk_bf16_f32 v178, v120, v121
	v_cvt_pk_bf16_f32 v179, v122, v123
	v_mul_f32_e32 v150, v121, v121
	v_mul_f32_e32 v140, v123, v123
	v_permlane16_swap_b32 v176, v178
	v_permlane16_swap_b32 v177, v179
	global_store_dwordx4 v165, v[176:179], s[38:39] sc1
	v_fmac_f32_e32 v150, v120, v120
	v_fmac_f32_e32 v140, v122, v122
	v_add_f32_e32 v150, v150, v140
	v_add_f32_e32 v246, v246, v150
	global_load_dwordx4 v[186:189], v158, s[36:37] offset:64
	s_waitcnt vmcnt(18)
	v_add_f32_e32 v116, v116, v190
	v_add_f32_e32 v117, v117, v191
	v_add_f32_e32 v118, v118, v192
	v_add_f32_e32 v119, v119, v193
	global_store_dwordx4 v154, v[116:119], s[30:31] offset:512 sc1
	v_cvt_pk_bf16_f32 v176, v116, v117
	v_cvt_pk_bf16_f32 v177, v118, v119
	v_mul_f32_e32 v150, v117, v117
	v_mul_f32_e32 v140, v119, v119
	v_fmac_f32_e32 v150, v116, v116
	v_fmac_f32_e32 v140, v118, v118
	v_add_f32_e32 v150, v150, v140
	v_add_f32_e32 v246, v246, v150
	global_load_dwordx4 v[190:193], v158, s[36:37] offset:512
	s_waitcnt vmcnt(19)
	v_add_f32_e32 v112, v112, v194
	v_add_f32_e32 v113, v113, v195
	v_add_f32_e32 v114, v114, v196
	v_add_f32_e32 v115, v115, v197
	global_store_dwordx4 v154, v[112:115], s[30:31] offset:576 sc1
	v_cvt_pk_bf16_f32 v178, v112, v113
	v_cvt_pk_bf16_f32 v179, v114, v115
	v_mul_f32_e32 v150, v113, v113
	v_mul_f32_e32 v140, v115, v115
	v_permlane16_swap_b32 v176, v178
	v_permlane16_swap_b32 v177, v179
	global_store_dwordx4 v165, v[176:179], s[38:39] offset:256 sc1
	v_fmac_f32_e32 v150, v112, v112
	v_fmac_f32_e32 v140, v114, v114
	v_add_f32_e32 v150, v150, v140
	v_add_f32_e32 v246, v246, v150
	global_load_dwordx4 v[194:197], v158, s[36:37] offset:576
	s_waitcnt vmcnt(21)
	v_add_f32_e32 v108, v108, v198
	v_add_f32_e32 v109, v109, v199
	v_add_f32_e32 v110, v110, v200
	v_add_f32_e32 v111, v111, v201
	global_store_dwordx4 v155, v[108:111], s[30:31] sc1
	v_cvt_pk_bf16_f32 v176, v108, v109
	v_cvt_pk_bf16_f32 v177, v110, v111
	v_mul_f32_e32 v150, v109, v109
	v_mul_f32_e32 v140, v111, v111
	v_fmac_f32_e32 v150, v108, v108
	v_fmac_f32_e32 v140, v110, v110
	v_add_f32_e32 v247, v150, v140
	global_load_dwordx4 v[198:201], v159, s[36:37]
	s_waitcnt vmcnt(22)
	v_add_f32_e32 v104, v104, v202
	v_add_f32_e32 v105, v105, v203
	v_add_f32_e32 v106, v106, v204
	v_add_f32_e32 v107, v107, v205
	global_store_dwordx4 v155, v[104:107], s[30:31] offset:64 sc1
	v_cvt_pk_bf16_f32 v178, v104, v105
	v_cvt_pk_bf16_f32 v179, v106, v107
	v_mul_f32_e32 v150, v105, v105
	v_mul_f32_e32 v140, v107, v107
	v_permlane16_swap_b32 v176, v178
	v_permlane16_swap_b32 v177, v179
	global_store_dwordx4 v166, v[176:179], s[38:39] sc1
	v_fmac_f32_e32 v150, v104, v104
	v_fmac_f32_e32 v140, v106, v106
	v_add_f32_e32 v150, v150, v140
	v_add_f32_e32 v247, v247, v150
	global_load_dwordx4 v[202:205], v159, s[36:37] offset:64
	s_waitcnt vmcnt(24)
	v_add_f32_e32 v100, v100, v206
	v_add_f32_e32 v101, v101, v207
	v_add_f32_e32 v102, v102, v208
	v_add_f32_e32 v103, v103, v209
	global_store_dwordx4 v155, v[100:103], s[30:31] offset:512 sc1
	v_cvt_pk_bf16_f32 v176, v100, v101
	v_cvt_pk_bf16_f32 v177, v102, v103
	v_mul_f32_e32 v150, v101, v101
	v_mul_f32_e32 v140, v103, v103
	v_fmac_f32_e32 v150, v100, v100
	v_fmac_f32_e32 v140, v102, v102
	v_add_f32_e32 v150, v150, v140
	v_add_f32_e32 v247, v247, v150
	global_load_dwordx4 v[206:209], v159, s[36:37] offset:512
	s_waitcnt vmcnt(25)
	v_add_f32_e32 v96, v96, v210
	v_add_f32_e32 v97, v97, v211
	v_add_f32_e32 v98, v98, v212
	v_add_f32_e32 v99, v99, v213
	global_store_dwordx4 v155, v[96:99], s[30:31] offset:576 sc1
	v_cvt_pk_bf16_f32 v178, v96, v97
	v_cvt_pk_bf16_f32 v179, v98, v99
	v_mul_f32_e32 v150, v97, v97
	v_mul_f32_e32 v140, v99, v99
	v_permlane16_swap_b32 v176, v178
	v_permlane16_swap_b32 v177, v179
	global_store_dwordx4 v166, v[176:179], s[38:39] offset:256 sc1
	v_fmac_f32_e32 v150, v96, v96
	v_fmac_f32_e32 v140, v98, v98
	v_add_f32_e32 v150, v150, v140
	v_add_f32_e32 v247, v247, v150
	global_load_dwordx4 v[210:213], v159, s[36:37] offset:576
	s_waitcnt vmcnt(27)
	v_add_f32_e32 v92, v92, v214
	v_add_f32_e32 v93, v93, v215
	v_add_f32_e32 v94, v94, v216
	v_add_f32_e32 v95, v95, v217
	global_store_dwordx4 v156, v[92:95], s[30:31] sc1
	v_cvt_pk_bf16_f32 v176, v92, v93
	v_cvt_pk_bf16_f32 v177, v94, v95
	v_mul_f32_e32 v150, v93, v93
	v_mul_f32_e32 v140, v95, v95
	v_fmac_f32_e32 v150, v92, v92
	v_fmac_f32_e32 v140, v94, v94
	v_add_f32_e32 v248, v150, v140
	global_load_dwordx4 v[214:217], v160, s[36:37]
	s_waitcnt vmcnt(28)
	v_add_f32_e32 v88, v88, v218
	v_add_f32_e32 v89, v89, v219
	v_add_f32_e32 v90, v90, v220
	v_add_f32_e32 v91, v91, v221
	global_store_dwordx4 v156, v[88:91], s[30:31] offset:64 sc1
	v_cvt_pk_bf16_f32 v178, v88, v89
	v_cvt_pk_bf16_f32 v179, v90, v91
	v_mul_f32_e32 v150, v89, v89
	v_mul_f32_e32 v140, v91, v91
	v_permlane16_swap_b32 v176, v178
	v_permlane16_swap_b32 v177, v179
	global_store_dwordx4 v167, v[176:179], s[38:39] sc1
	v_fmac_f32_e32 v150, v88, v88
	v_fmac_f32_e32 v140, v90, v90
	v_add_f32_e32 v150, v150, v140
	v_add_f32_e32 v248, v248, v150
	global_load_dwordx4 v[218:221], v160, s[36:37] offset:64
	s_waitcnt vmcnt(30)
	v_add_f32_e32 v84, v84, v222
	v_add_f32_e32 v85, v85, v223
	v_add_f32_e32 v86, v86, v224
	v_add_f32_e32 v87, v87, v225
	global_store_dwordx4 v156, v[84:87], s[30:31] offset:512 sc1
	v_cvt_pk_bf16_f32 v176, v84, v85
	v_cvt_pk_bf16_f32 v177, v86, v87
	v_mul_f32_e32 v150, v85, v85
	v_mul_f32_e32 v140, v87, v87
	v_fmac_f32_e32 v150, v84, v84
	v_fmac_f32_e32 v140, v86, v86
	v_add_f32_e32 v150, v150, v140
	v_add_f32_e32 v248, v248, v150
	global_load_dwordx4 v[222:225], v160, s[36:37] offset:512
	s_waitcnt vmcnt(31)
	v_add_f32_e32 v80, v80, v226
	v_add_f32_e32 v81, v81, v227
	v_add_f32_e32 v82, v82, v228
	v_add_f32_e32 v83, v83, v229
	global_store_dwordx4 v156, v[80:83], s[30:31] offset:576 sc1
	v_cvt_pk_bf16_f32 v178, v80, v81
	v_cvt_pk_bf16_f32 v179, v82, v83
	v_mul_f32_e32 v150, v81, v81
	v_mul_f32_e32 v140, v83, v83
	v_permlane16_swap_b32 v176, v178
	v_permlane16_swap_b32 v177, v179
	global_store_dwordx4 v167, v[176:179], s[38:39] offset:256 sc1
	v_fmac_f32_e32 v150, v80, v80
	v_fmac_f32_e32 v140, v82, v82
	v_add_f32_e32 v150, v150, v140
	v_add_f32_e32 v248, v248, v150
	global_load_dwordx4 v[226:229], v160, s[36:37] offset:576
	s_waitcnt vmcnt(33)
	v_add_f32_e32 v76, v76, v230
	v_add_f32_e32 v77, v77, v231
	v_add_f32_e32 v78, v78, v232
	v_add_f32_e32 v79, v79, v233
	global_store_dwordx4 v157, v[76:79], s[30:31] sc1
	v_cvt_pk_bf16_f32 v176, v76, v77
	v_cvt_pk_bf16_f32 v177, v78, v79
	v_mul_f32_e32 v150, v77, v77
	v_mul_f32_e32 v140, v79, v79
	v_fmac_f32_e32 v150, v76, v76
	v_fmac_f32_e32 v140, v78, v78
	v_add_f32_e32 v249, v150, v140
	global_load_dwordx4 v[230:233], v161, s[36:37]
	s_waitcnt vmcnt(34)
	v_add_f32_e32 v72, v72, v234
	v_add_f32_e32 v73, v73, v235
	v_add_f32_e32 v74, v74, v236
	v_add_f32_e32 v75, v75, v237
	global_store_dwordx4 v157, v[72:75], s[30:31] offset:64 sc1
	v_cvt_pk_bf16_f32 v178, v72, v73
	v_cvt_pk_bf16_f32 v179, v74, v75
	v_mul_f32_e32 v150, v73, v73
	v_mul_f32_e32 v140, v75, v75
	v_permlane16_swap_b32 v176, v178
	v_permlane16_swap_b32 v177, v179
	global_store_dwordx4 v168, v[176:179], s[38:39] sc1
	v_fmac_f32_e32 v150, v72, v72
	v_fmac_f32_e32 v140, v74, v74
	v_add_f32_e32 v150, v150, v140
	v_add_f32_e32 v249, v249, v150
	global_load_dwordx4 v[234:237], v161, s[36:37] offset:64
	s_waitcnt vmcnt(36)
	v_add_f32_e32 v68, v68, v238
	v_add_f32_e32 v69, v69, v239
	v_add_f32_e32 v70, v70, v240
	v_add_f32_e32 v71, v71, v241
	global_store_dwordx4 v157, v[68:71], s[30:31] offset:512 sc1
	v_cvt_pk_bf16_f32 v176, v68, v69
	v_cvt_pk_bf16_f32 v177, v70, v71
	v_mul_f32_e32 v150, v69, v69
	v_mul_f32_e32 v140, v71, v71
	v_fmac_f32_e32 v150, v68, v68
	v_fmac_f32_e32 v140, v70, v70
	v_add_f32_e32 v150, v150, v140
	v_add_f32_e32 v249, v249, v150
	global_load_dwordx4 v[238:241], v161, s[36:37] offset:512
	s_waitcnt vmcnt(37)
	v_add_f32_e32 v64, v64, v242
	v_add_f32_e32 v65, v65, v243
	v_add_f32_e32 v66, v66, v244
	v_add_f32_e32 v67, v67, v245
	global_store_dwordx4 v157, v[64:67], s[30:31] offset:576 sc1
	v_cvt_pk_bf16_f32 v178, v64, v65
	v_cvt_pk_bf16_f32 v179, v66, v67
	v_mul_f32_e32 v150, v65, v65
	v_mul_f32_e32 v140, v67, v67
	v_permlane16_swap_b32 v176, v178
	v_permlane16_swap_b32 v177, v179
	global_store_dwordx4 v168, v[176:179], s[38:39] offset:256 sc1
	v_fmac_f32_e32 v150, v64, v64
	v_fmac_f32_e32 v140, v66, v66
	v_add_f32_e32 v150, v150, v140
	v_add_f32_e32 v249, v249, v150
	global_load_dwordx4 v[242:245], v161, s[36:37] offset:576
	s_waitcnt vmcnt(38)
	v_add_f32_e32 v60, v60, v182
	v_add_f32_e32 v61, v61, v183
	v_add_f32_e32 v62, v62, v184
	v_add_f32_e32 v63, v63, v185
	global_store_dwordx4 v158, v[60:63], s[30:31] sc1
	v_cvt_pk_bf16_f32 v176, v60, v61
	v_cvt_pk_bf16_f32 v177, v62, v63
	v_mul_f32_e32 v150, v61, v61
	v_mul_f32_e32 v140, v63, v63
	v_fmac_f32_e32 v150, v60, v60
	v_fmac_f32_e32 v140, v62, v62
	v_add_f32_e32 v250, v150, v140
	s_waitcnt vmcnt(36)
	v_add_f32_e32 v56, v56, v186
	v_add_f32_e32 v57, v57, v187
	v_add_f32_e32 v58, v58, v188
	v_add_f32_e32 v59, v59, v189
	global_store_dwordx4 v158, v[56:59], s[30:31] offset:64 sc1
	v_cvt_pk_bf16_f32 v178, v56, v57
	v_cvt_pk_bf16_f32 v179, v58, v59
	v_mul_f32_e32 v150, v57, v57
	v_mul_f32_e32 v140, v59, v59
	v_permlane16_swap_b32 v176, v178
	v_permlane16_swap_b32 v177, v179
	global_store_dwordx4 v169, v[176:179], s[38:39] sc1
	v_fmac_f32_e32 v150, v56, v56
	v_fmac_f32_e32 v140, v58, v58
	v_add_f32_e32 v150, v150, v140
	v_add_f32_e32 v250, v250, v150
	s_waitcnt vmcnt(36)
	v_add_f32_e32 v52, v52, v190
	v_add_f32_e32 v53, v53, v191
	v_add_f32_e32 v54, v54, v192
	v_add_f32_e32 v55, v55, v193
	global_store_dwordx4 v158, v[52:55], s[30:31] offset:512 sc1
	v_cvt_pk_bf16_f32 v176, v52, v53
	v_cvt_pk_bf16_f32 v177, v54, v55
	v_mul_f32_e32 v150, v53, v53
	v_mul_f32_e32 v140, v55, v55
	v_fmac_f32_e32 v150, v52, v52
	v_fmac_f32_e32 v140, v54, v54
	v_add_f32_e32 v150, v150, v140
	v_add_f32_e32 v250, v250, v150
	s_waitcnt vmcnt(34)
	v_add_f32_e32 v48, v48, v194
	v_add_f32_e32 v49, v49, v195
	v_add_f32_e32 v50, v50, v196
	v_add_f32_e32 v51, v51, v197
	global_store_dwordx4 v158, v[48:51], s[30:31] offset:576 sc1
	v_cvt_pk_bf16_f32 v178, v48, v49
	v_cvt_pk_bf16_f32 v179, v50, v51
	v_mul_f32_e32 v150, v49, v49
	v_mul_f32_e32 v140, v51, v51
	v_permlane16_swap_b32 v176, v178
	v_permlane16_swap_b32 v177, v179
	global_store_dwordx4 v169, v[176:179], s[38:39] offset:256 sc1
	v_fmac_f32_e32 v150, v48, v48
	v_fmac_f32_e32 v140, v50, v50
	v_add_f32_e32 v150, v150, v140
	v_add_f32_e32 v250, v250, v150
	s_waitcnt vmcnt(34)
	v_add_f32_e32 v44, v44, v198
	v_add_f32_e32 v45, v45, v199
	v_add_f32_e32 v46, v46, v200
	v_add_f32_e32 v47, v47, v201
	global_store_dwordx4 v159, v[44:47], s[30:31] sc1
	v_cvt_pk_bf16_f32 v176, v44, v45
	v_cvt_pk_bf16_f32 v177, v46, v47
	v_mul_f32_e32 v150, v45, v45
	v_mul_f32_e32 v140, v47, v47
	v_fmac_f32_e32 v150, v44, v44
	v_fmac_f32_e32 v140, v46, v46
	v_add_f32_e32 v251, v150, v140
	s_waitcnt vmcnt(32)
	v_add_f32_e32 v40, v40, v202
	v_add_f32_e32 v41, v41, v203
	v_add_f32_e32 v42, v42, v204
	v_add_f32_e32 v43, v43, v205
	global_store_dwordx4 v159, v[40:43], s[30:31] offset:64 sc1
	v_cvt_pk_bf16_f32 v178, v40, v41
	v_cvt_pk_bf16_f32 v179, v42, v43
	v_mul_f32_e32 v150, v41, v41
	v_mul_f32_e32 v140, v43, v43
	v_permlane16_swap_b32 v176, v178
	v_permlane16_swap_b32 v177, v179
	global_store_dwordx4 v170, v[176:179], s[38:39] sc1
	v_fmac_f32_e32 v150, v40, v40
	v_fmac_f32_e32 v140, v42, v42
	v_add_f32_e32 v150, v150, v140
	v_add_f32_e32 v251, v251, v150
	s_waitcnt vmcnt(32)
	v_add_f32_e32 v36, v36, v206
	v_add_f32_e32 v37, v37, v207
	v_add_f32_e32 v38, v38, v208
	v_add_f32_e32 v39, v39, v209
	global_store_dwordx4 v159, v[36:39], s[30:31] offset:512 sc1
	v_cvt_pk_bf16_f32 v176, v36, v37
	v_cvt_pk_bf16_f32 v177, v38, v39
	v_mul_f32_e32 v150, v37, v37
	v_mul_f32_e32 v140, v39, v39
	v_fmac_f32_e32 v150, v36, v36
	v_fmac_f32_e32 v140, v38, v38
	v_add_f32_e32 v150, v150, v140
	v_add_f32_e32 v251, v251, v150
	s_waitcnt vmcnt(30)
	v_add_f32_e32 v32, v32, v210
	v_add_f32_e32 v33, v33, v211
	v_add_f32_e32 v34, v34, v212
	v_add_f32_e32 v35, v35, v213
	global_store_dwordx4 v159, v[32:35], s[30:31] offset:576 sc1
	v_cvt_pk_bf16_f32 v178, v32, v33
	v_cvt_pk_bf16_f32 v179, v34, v35
	v_mul_f32_e32 v150, v33, v33
	v_mul_f32_e32 v140, v35, v35
	v_permlane16_swap_b32 v176, v178
	v_permlane16_swap_b32 v177, v179
	global_store_dwordx4 v170, v[176:179], s[38:39] offset:256 sc1
	v_fmac_f32_e32 v150, v32, v32
	v_fmac_f32_e32 v140, v34, v34
	v_add_f32_e32 v150, v150, v140
	v_add_f32_e32 v251, v251, v150
	s_waitcnt vmcnt(30)
	v_add_f32_e32 v28, v28, v214
	v_add_f32_e32 v29, v29, v215
	v_add_f32_e32 v30, v30, v216
	v_add_f32_e32 v31, v31, v217
	global_store_dwordx4 v160, v[28:31], s[30:31] sc1
	v_cvt_pk_bf16_f32 v176, v28, v29
	v_cvt_pk_bf16_f32 v177, v30, v31
	v_mul_f32_e32 v150, v29, v29
	v_mul_f32_e32 v140, v31, v31
	v_fmac_f32_e32 v150, v28, v28
	v_fmac_f32_e32 v140, v30, v30
	v_add_f32_e32 v252, v150, v140
	s_waitcnt vmcnt(28)
	v_add_f32_e32 v24, v24, v218
	v_add_f32_e32 v25, v25, v219
	v_add_f32_e32 v26, v26, v220
	v_add_f32_e32 v27, v27, v221
	global_store_dwordx4 v160, v[24:27], s[30:31] offset:64 sc1
	v_cvt_pk_bf16_f32 v178, v24, v25
	v_cvt_pk_bf16_f32 v179, v26, v27
	v_mul_f32_e32 v150, v25, v25
	v_mul_f32_e32 v140, v27, v27
	v_permlane16_swap_b32 v176, v178
	v_permlane16_swap_b32 v177, v179
	global_store_dwordx4 v171, v[176:179], s[38:39] sc1
	v_fmac_f32_e32 v150, v24, v24
	v_fmac_f32_e32 v140, v26, v26
	v_add_f32_e32 v150, v150, v140
	v_add_f32_e32 v252, v252, v150
	s_waitcnt vmcnt(28)
	v_add_f32_e32 v20, v20, v222
	v_add_f32_e32 v21, v21, v223
	v_add_f32_e32 v22, v22, v224
	v_add_f32_e32 v23, v23, v225
	global_store_dwordx4 v160, v[20:23], s[30:31] offset:512 sc1
	v_cvt_pk_bf16_f32 v176, v20, v21
	v_cvt_pk_bf16_f32 v177, v22, v23
	v_mul_f32_e32 v150, v21, v21
	v_mul_f32_e32 v140, v23, v23
	v_fmac_f32_e32 v150, v20, v20
	v_fmac_f32_e32 v140, v22, v22
	v_add_f32_e32 v150, v150, v140
	v_add_f32_e32 v252, v252, v150
	s_waitcnt vmcnt(26)
	v_add_f32_e32 v16, v16, v226
	v_add_f32_e32 v17, v17, v227
	v_add_f32_e32 v18, v18, v228
	v_add_f32_e32 v19, v19, v229
	global_store_dwordx4 v160, v[16:19], s[30:31] offset:576 sc1
	v_cvt_pk_bf16_f32 v178, v16, v17
	v_cvt_pk_bf16_f32 v179, v18, v19
	v_mul_f32_e32 v150, v17, v17
	v_mul_f32_e32 v140, v19, v19
	v_permlane16_swap_b32 v176, v178
	v_permlane16_swap_b32 v177, v179
	global_store_dwordx4 v171, v[176:179], s[38:39] offset:256 sc1
	v_fmac_f32_e32 v150, v16, v16
	v_fmac_f32_e32 v140, v18, v18
	v_add_f32_e32 v150, v150, v140
	v_add_f32_e32 v252, v252, v150
	s_waitcnt vmcnt(26)
	v_add_f32_e32 v12, v12, v230
	v_add_f32_e32 v13, v13, v231
	v_add_f32_e32 v14, v14, v232
	v_add_f32_e32 v15, v15, v233
	global_store_dwordx4 v161, v[12:15], s[30:31] sc1
	v_cvt_pk_bf16_f32 v176, v12, v13
	v_cvt_pk_bf16_f32 v177, v14, v15
	v_mul_f32_e32 v150, v13, v13
	v_mul_f32_e32 v140, v15, v15
	v_fmac_f32_e32 v150, v12, v12
	v_fmac_f32_e32 v140, v14, v14
	v_add_f32_e32 v253, v150, v140
	s_waitcnt vmcnt(24)
	v_add_f32_e32 v8, v8, v234
	v_add_f32_e32 v9, v9, v235
	v_add_f32_e32 v10, v10, v236
	v_add_f32_e32 v11, v11, v237
	global_store_dwordx4 v161, v[8:11], s[30:31] offset:64 sc1
	v_cvt_pk_bf16_f32 v178, v8, v9
	v_cvt_pk_bf16_f32 v179, v10, v11
	v_mul_f32_e32 v150, v9, v9
	v_mul_f32_e32 v140, v11, v11
	v_permlane16_swap_b32 v176, v178
	v_permlane16_swap_b32 v177, v179
	global_store_dwordx4 v172, v[176:179], s[38:39] sc1
	v_fmac_f32_e32 v150, v8, v8
	v_fmac_f32_e32 v140, v10, v10
	v_add_f32_e32 v150, v150, v140
	v_add_f32_e32 v253, v253, v150
	s_waitcnt vmcnt(24)
	v_add_f32_e32 v4, v4, v238
	v_add_f32_e32 v5, v5, v239
	v_add_f32_e32 v6, v6, v240
	v_add_f32_e32 v7, v7, v241
	global_store_dwordx4 v161, v[4:7], s[30:31] offset:512 sc1
	v_cvt_pk_bf16_f32 v176, v4, v5
	v_cvt_pk_bf16_f32 v177, v6, v7
	v_mul_f32_e32 v150, v5, v5
	v_mul_f32_e32 v140, v7, v7
	v_fmac_f32_e32 v150, v4, v4
	v_fmac_f32_e32 v140, v6, v6
	v_add_f32_e32 v150, v150, v140
	v_add_f32_e32 v253, v253, v150
	s_waitcnt vmcnt(22)
	v_add_f32_e32 v0, v0, v242
	v_add_f32_e32 v1, v1, v243
	v_add_f32_e32 v2, v2, v244
	v_add_f32_e32 v3, v3, v245
	global_store_dwordx4 v161, v[0:3], s[30:31] offset:576 sc1
	v_cvt_pk_bf16_f32 v178, v0, v1
	v_cvt_pk_bf16_f32 v179, v2, v3
	v_mul_f32_e32 v150, v1, v1
	v_mul_f32_e32 v140, v3, v3
	v_permlane16_swap_b32 v176, v178
	v_permlane16_swap_b32 v177, v179
	global_store_dwordx4 v172, v[176:179], s[38:39] offset:256 sc1
	v_fmac_f32_e32 v150, v0, v0
	v_fmac_f32_e32 v140, v2, v2
	v_add_f32_e32 v150, v150, v140
	v_add_f32_e32 v253, v253, v150
	ds_bpermute_b32 v182, v173, v246
	ds_bpermute_b32 v183, v173, v247
	ds_bpermute_b32 v184, v173, v248
	ds_bpermute_b32 v185, v173, v249
	ds_bpermute_b32 v186, v173, v250
	ds_bpermute_b32 v187, v173, v251
	ds_bpermute_b32 v188, v173, v252
	ds_bpermute_b32 v189, v173, v253
	s_waitcnt lgkmcnt(0)
	v_add_f32_e32 v246, v246, v182
	v_add_f32_e32 v247, v247, v183
	v_add_f32_e32 v248, v248, v184
	v_add_f32_e32 v249, v249, v185
	v_add_f32_e32 v250, v250, v186
	v_add_f32_e32 v251, v251, v187
	v_add_f32_e32 v252, v252, v188
	v_add_f32_e32 v253, v253, v189
	ds_bpermute_b32 v182, v174, v246
	ds_bpermute_b32 v183, v174, v247
	ds_bpermute_b32 v184, v174, v248
	ds_bpermute_b32 v185, v174, v249
	ds_bpermute_b32 v186, v174, v250
	ds_bpermute_b32 v187, v174, v251
	ds_bpermute_b32 v188, v174, v252
	ds_bpermute_b32 v189, v174, v253
	s_waitcnt lgkmcnt(0)
	v_add_f32_e32 v246, v246, v182
	v_add_f32_e32 v247, v247, v183
	v_add_f32_e32 v248, v248, v184
	v_add_f32_e32 v249, v249, v185
	v_add_f32_e32 v250, v250, v186
	v_add_f32_e32 v251, v251, v187
	v_add_f32_e32 v252, v252, v188
	v_add_f32_e32 v253, v253, v189
	s_and_saveexec_b64 s[50:51], s[6:7]
	global_store_dword v180, v246, s[40:41] sc1
	global_store_dword v180, v247, s[40:41] offset:1024 sc1
	global_store_dword v180, v248, s[40:41] offset:2048 sc1
	global_store_dword v180, v249, s[40:41] offset:3072 sc1
	global_store_dword v175, v250, s[40:41] sc1
	global_store_dword v175, v251, s[40:41] offset:1024 sc1
	global_store_dword v175, v252, s[40:41] offset:2048 sc1
	global_store_dword v175, v253, s[40:41] offset:3072 sc1
